# non-aligned epilogue mode for the two bf16-output GEMM phases only (P2, P7): the leading half runs its VALU/store-bound epilogue under the trailing half's last MFMA block
# baseline (speedup 1.0000x reference)
; #define PG8_STAGE(bufoff, gbase, voff) do { _Pragma("unroll") for (int _i = 0; _i < 2; ++_i) \
;         __builtin_amdgcn_global_load_lds((const unsigned*)((const char*)(gbase) + (voff)[_i]), (PG8_LAS unsigned*)(lds + (bufoff) + ldsw + _i * 8192), 16, 0, 0); } while (0)
; #define PG8_LDA(dst, b, h) do { _Pragma("unroll") for (int m = 0; m < 4; ++m) _Pragma("unroll") for (int k = 0; k < 2; ++k) dst[m][k] = *(const PG8_LAS bf16x8*)(lds + PG8_SA(b, h) + aoff + m * 2048 + k * 1024); } while (0)
; #define PG8_LDB(dst, b, h) do { _Pragma("unroll") for (int n = 0; n < 2; ++n) _Pragma("unroll") for (int k = 0; k < 2; ++k) dst[n][k] = *(const PG8_LAS bf16x8*)(lds + PG8_SB(b, h) + boff + n * 2048 + k * 1024); } while (0)
; #define PG8_MMA(ai, bj, At, Bt) do { __builtin_amdgcn_s_setprio(1); _Pragma("unroll") for (int m = 0; m < 4; ++m) _Pragma("unroll") for (int n = 0; n < 2; ++n) _Pragma("unroll") for (int k = 0; k < 2; ++k) \
;         acc[ai][bj][m][n] = __builtin_amdgcn_mfma_f32_16x16x32_bf16(Bt[n][k], At[m][k], acc[ai][bj][m][n], 0, 0, 0); __builtin_amdgcn_s_setprio(0); } while (0)
; #define PG8_WAIT_V(n) asm volatile("s_waitcnt vmcnt(" #n ")" ::: "memory")
; #define PG8_WAIT_L(n) asm volatile("s_waitcnt lgkmcnt(" #n ")" ::: "memory")
; template <class Epi, class Sched, bool ALIGN_EPI = false, bool SP2 = false>
; __device__ __forceinline__ void gemm_phase(PG8_LAS unsigned char* lds, const Gemm g, const Sched& S, const Epi& E) {
;     ...
;             const bool last = (t == nt - 2);
;             const char* a1 = cA + (size_t)(t + 1) * kstep;
;             const char* a2 = last ? nA : cA + (size_t)(t + 2) * kstep; const char* b2 = last ? nB : cB + (size_t)(t + 2) * kstep;
;             const char* a3 = a2 + kstep; const char* b3 = b2 + kstep;
;             if (last && has_next) S.a_ready(nxt);
;             if constexpr (SP2) {
;             PG8_LDB(B0, 0, 0); PG8_LDB(B1, 0, 1); PG8_SCHED; PG8_LDA(At, 0, 0); PG8_STAGE(PG8_SA(1, 1), a1 + hstep, voffA);
;             PG8_WAIT_V(8); PG8_WAIT_L(0); PG8_BAR; PG8_MMA(0, 0, At, B0); PG8_MMA(0, 1, At, B1); PG8_BAR; PG8_SCHED;
;             PG8_LDA(At, 0, 1); PG8_STAGE(PG8_SB(0, 0), b2, voffB); PG8_STAGE(PG8_SB(0, 1), b2 + hstep, voffB); PG8_STAGE(PG8_SA(0, 0), a2, voffA);
;             PG8_WAIT_V(8); PG8_WAIT_L(0); PG8_BAR; PG8_MMA(1, 0, At, B0); PG8_MMA(1, 1, At, B1); PG8_BAR; PG8_SCHED;
.LBB0_205:
	ds_read_b128 v[128:131], v190
	ds_read_b128 v[132:135], v190 offset:1024
	ds_read_b128 v[136:139], v190 offset:2048
	ds_read_b128 v[140:143], v190 offset:3072
	ds_read_b128 v[144:147], v191
	ds_read_b128 v[148:151], v191 offset:1024
	ds_read_b128 v[152:155], v191 offset:2048
	ds_read_b128 v[156:159], v191 offset:3072
	s_add_u32 s6, s4, 0xfff80080
	s_addc_u32 s7, s5, -1
	s_cmp_eq_u32 s51, 28
	s_cselect_b32 s29, s1, s7
	s_cselect_b32 s28, s3, s6
	s_cselect_b32 s7, s21, s50
	s_cselect_b32 s6, s23, s33
	v_lshl_add_u64 v[184:185], s[4:5], 0, v[172:173]
	s_add_i32 m0, s31, 0xc000
	ds_read_b128 v[180:183], v192
	ds_read_b128 v[194:197], v192 offset:1024
	ds_read_b128 v[198:201], v192 offset:2048
	ds_read_b128 v[202:205], v192 offset:3072
	ds_read_b128 v[206:209], v192 offset:4096
	ds_read_b128 v[210:213], v192 offset:5120
	ds_read_b128 v[214:217], v192 offset:6144
	ds_read_b128 v[218:221], v192 offset:7168
	global_load_lds_dwordx4 v[184:185], off
	v_lshl_add_u64 v[184:185], s[4:5], 0, v[174:175]
	s_add_i32 m0, s31, 0xe000
	s_nop 0
	global_load_lds_dwordx4 v[184:185], off
	s_setprio 1
	s_waitcnt vmcnt(8)
	s_waitcnt lgkmcnt(0)
	s_barrier
	v_mfma_f32_16x16x32_bf16 v[124:127], v[128:131], v[180:183], v[124:127]
	v_mfma_f32_16x16x32_bf16 v[120:123], v[136:139], v[180:183], v[120:123]
	v_mfma_f32_16x16x32_bf16 v[108:111], v[128:131], v[198:201], v[108:111]
	v_mfma_f32_16x16x32_bf16 v[104:107], v[136:139], v[198:201], v[104:107]
	v_mfma_f32_16x16x32_bf16 v[92:95], v[128:131], v[206:209], v[92:95]
	v_mfma_f32_16x16x32_bf16 v[88:91], v[136:139], v[206:209], v[88:91]
	v_mfma_f32_16x16x32_bf16 v[76:79], v[128:131], v[214:217], v[76:79]
	v_mfma_f32_16x16x32_bf16 v[72:75], v[136:139], v[214:217], v[72:75]
	v_mfma_f32_16x16x32_bf16 v[124:127], v[132:135], v[194:197], v[124:127]
	v_mfma_f32_16x16x32_bf16 v[120:123], v[140:143], v[194:197], v[120:123]
	v_mfma_f32_16x16x32_bf16 v[108:111], v[132:135], v[202:205], v[108:111]
	v_mfma_f32_16x16x32_bf16 v[104:107], v[140:143], v[202:205], v[104:107]
	v_mfma_f32_16x16x32_bf16 v[92:95], v[132:135], v[210:213], v[92:95]
	v_mfma_f32_16x16x32_bf16 v[88:91], v[140:143], v[210:213], v[88:91]
	v_mfma_f32_16x16x32_bf16 v[76:79], v[132:135], v[218:221], v[76:79]
	v_mfma_f32_16x16x32_bf16 v[72:75], v[140:143], v[218:221], v[72:75]
	s_setprio 0
	s_setprio 1
	v_mfma_f32_16x16x32_bf16 v[116:119], v[144:147], v[180:183], v[116:119]
	v_mfma_f32_16x16x32_bf16 v[112:115], v[152:155], v[180:183], v[112:115]
	v_mfma_f32_16x16x32_bf16 v[100:103], v[144:147], v[198:201], v[100:103]
	v_mfma_f32_16x16x32_bf16 v[96:99], v[152:155], v[198:201], v[96:99]
	v_mfma_f32_16x16x32_bf16 v[84:87], v[144:147], v[206:209], v[84:87]
	v_mfma_f32_16x16x32_bf16 v[80:83], v[152:155], v[206:209], v[80:83]
	v_mfma_f32_16x16x32_bf16 v[68:71], v[144:147], v[214:217], v[68:71]
	v_mfma_f32_16x16x32_bf16 v[64:67], v[152:155], v[214:217], v[64:67]
	v_mfma_f32_16x16x32_bf16 v[116:119], v[148:151], v[194:197], v[116:119]
	v_mfma_f32_16x16x32_bf16 v[112:115], v[156:159], v[194:197], v[112:115]
	v_mfma_f32_16x16x32_bf16 v[100:103], v[148:151], v[202:205], v[100:103]
	v_mfma_f32_16x16x32_bf16 v[96:99], v[156:159], v[202:205], v[96:99]
	v_mfma_f32_16x16x32_bf16 v[84:87], v[148:151], v[210:213], v[84:87]
	v_mfma_f32_16x16x32_bf16 v[80:83], v[156:159], v[210:213], v[80:83]
	v_mfma_f32_16x16x32_bf16 v[68:71], v[148:151], v[218:221], v[68:71]
	v_mfma_f32_16x16x32_bf16 v[64:67], v[156:159], v[218:221], v[64:67]
	s_barrier
	s_setprio 0
	s_add_i32 s52, s43, s30
	v_lshl_add_u64 v[184:185], s[6:7], 0, v[164:165]
	s_mov_b32 m0, s52
	ds_read_b128 v[180:183], v192 offset:16384
	ds_read_b128 v[194:197], v192 offset:17408
	ds_read_b128 v[198:201], v192 offset:18432
	ds_read_b128 v[202:205], v192 offset:19456
	ds_read_b128 v[206:209], v192 offset:20480
	ds_read_b128 v[210:213], v192 offset:21504
	ds_read_b128 v[214:217], v192 offset:22528
	ds_read_b128 v[218:221], v192 offset:23552
	global_load_lds_dwordx4 v[184:185], off
	s_add_i32 m0, s52, 0x2000
	s_add_u32 s52, s6, 0x80000
	v_lshl_add_u64 v[222:223], s[6:7], 0, v[168:169]
	s_addc_u32 s53, s7, 0
	s_add_i32 s54, s44, s30
	global_load_lds_dwordx4 v[222:223], off
	v_lshl_add_u64 v[224:225], s[52:53], 0, v[164:165]
	s_mov_b32 m0, s54
	v_lshl_add_u64 v[226:227], s[28:29], 0, v[166:167]
	global_load_lds_dwordx4 v[224:225], off
	v_lshl_add_u64 v[224:225], s[52:53], 0, v[168:169]
	s_add_i32 m0, s54, 0x2000
	s_nop 0
	global_load_lds_dwordx4 v[224:225], off
	v_lshl_add_u64 v[224:225], s[28:29], 0, v[162:163]
	s_mov_b32 m0, s31
	s_nop 0
	global_load_lds_dwordx4 v[224:225], off
	s_mov_b32 m0, s34
	s_nop 0
	global_load_lds_dwordx4 v[226:227], off
	s_setprio 1
	s_waitcnt vmcnt(8)
	s_waitcnt lgkmcnt(0)
	s_barrier
; #define PG8_STAGE(bufoff, gbase, voff) do { _Pragma("unroll") for (int _i = 0; _i < 2; ++_i) \
;         __builtin_amdgcn_global_load_lds((const unsigned*)((const char*)(gbase) + (voff)[_i]), (PG8_LAS unsigned*)(lds + (bufoff) + ldsw + _i * 8192), 16, 0, 0); } while (0)
; #define PG8_LDA(dst, b, h) do { _Pragma("unroll") for (int m = 0; m < 4; ++m) _Pragma("unroll") for (int k = 0; k < 2; ++k) dst[m][k] = *(const PG8_LAS bf16x8*)(lds + PG8_SA(b, h) + aoff + m * 2048 + k * 1024); } while (0)
; #define PG8_LDB(dst, b, h) do { _Pragma("unroll") for (int n = 0; n < 2; ++n) _Pragma("unroll") for (int k = 0; k < 2; ++k) dst[n][k] = *(const PG8_LAS bf16x8*)(lds + PG8_SB(b, h) + boff + n * 2048 + k * 1024); } while (0)
; #define PG8_MMA(ai, bj, At, Bt) do { __builtin_amdgcn_s_setprio(1); _Pragma("unroll") for (int m = 0; m < 4; ++m) _Pragma("unroll") for (int n = 0; n < 2; ++n) _Pragma("unroll") for (int k = 0; k < 2; ++k) \
;         acc[ai][bj][m][n] = __builtin_amdgcn_mfma_f32_16x16x32_bf16(Bt[n][k], At[m][k], acc[ai][bj][m][n], 0, 0, 0); __builtin_amdgcn_s_setprio(0); } while (0)
; #define PG8_WAIT_V(n) asm volatile("s_waitcnt vmcnt(" #n ")" ::: "memory")
; #define PG8_WAIT_L(n) asm volatile("s_waitcnt lgkmcnt(" #n ")" ::: "memory")
; #define PG8_BAR __builtin_amdgcn_s_barrier()
; #define PG8_SCHED __builtin_amdgcn_sched_barrier(0)
; template <class Epi, class Sched, bool ALIGN_EPI = false, bool SP2 = false>
; __device__ __forceinline__ void gemm_phase(PG8_LAS unsigned char* lds, const Gemm g, const Sched& S, const Epi& E) {
;     ...
;             PG8_WAIT_V(8); PG8_WAIT_L(0); PG8_BAR; PG8_MMA(1, 0, At, B0); PG8_MMA(1, 1, At, B1); PG8_BAR; PG8_SCHED;
;             PG8_LDB(B0, 1, 0); PG8_LDB(B1, 1, 1); PG8_SCHED; PG8_LDA(At, 1, 0); PG8_STAGE(PG8_SA(0, 1), a2 + hstep, voffA);
;             PG8_WAIT_V(8); PG8_WAIT_L(0); PG8_BAR; PG8_MMA(0, 0, At, B0); PG8_MMA(0, 1, At, B1); PG8_BAR; PG8_SCHED;
	v_mfma_f32_16x16x32_bf16 v[60:63], v[128:131], v[180:183], v[60:63]
	v_mfma_f32_16x16x32_bf16 v[56:59], v[136:139], v[180:183], v[56:59]
	v_mfma_f32_16x16x32_bf16 v[44:47], v[128:131], v[198:201], v[44:47]
	v_mfma_f32_16x16x32_bf16 v[40:43], v[136:139], v[198:201], v[40:43]
	v_mfma_f32_16x16x32_bf16 v[28:31], v[128:131], v[206:209], v[28:31]
	v_mfma_f32_16x16x32_bf16 v[24:27], v[136:139], v[206:209], v[24:27]
	v_mfma_f32_16x16x32_bf16 v[12:15], v[128:131], v[214:217], v[12:15]
	v_mfma_f32_16x16x32_bf16 v[8:11], v[136:139], v[214:217], v[8:11]
	v_mfma_f32_16x16x32_bf16 v[60:63], v[132:135], v[194:197], v[60:63]
	v_mfma_f32_16x16x32_bf16 v[56:59], v[140:143], v[194:197], v[56:59]
	v_mfma_f32_16x16x32_bf16 v[44:47], v[132:135], v[202:205], v[44:47]
	v_mfma_f32_16x16x32_bf16 v[40:43], v[140:143], v[202:205], v[40:43]
	v_mfma_f32_16x16x32_bf16 v[28:31], v[132:135], v[210:213], v[28:31]
	v_mfma_f32_16x16x32_bf16 v[24:27], v[140:143], v[210:213], v[24:27]
	v_mfma_f32_16x16x32_bf16 v[12:15], v[132:135], v[218:221], v[12:15]
	v_mfma_f32_16x16x32_bf16 v[8:11], v[140:143], v[218:221], v[8:11]
	s_setprio 0
	s_setprio 1
	v_mfma_f32_16x16x32_bf16 v[52:55], v[144:147], v[180:183], v[52:55]
	v_mfma_f32_16x16x32_bf16 v[48:51], v[152:155], v[180:183], v[48:51]
	v_mfma_f32_16x16x32_bf16 v[36:39], v[144:147], v[198:201], v[36:39]
	v_mfma_f32_16x16x32_bf16 v[32:35], v[152:155], v[198:201], v[32:35]
	v_mfma_f32_16x16x32_bf16 v[20:23], v[144:147], v[206:209], v[20:23]
	v_mfma_f32_16x16x32_bf16 v[16:19], v[152:155], v[206:209], v[16:19]
	v_mfma_f32_16x16x32_bf16 v[4:7], v[144:147], v[214:217], v[4:7]
	v_mfma_f32_16x16x32_bf16 v[0:3], v[152:155], v[214:217], v[0:3]
	v_mfma_f32_16x16x32_bf16 v[52:55], v[148:151], v[194:197], v[52:55]
	v_mfma_f32_16x16x32_bf16 v[48:51], v[156:159], v[194:197], v[48:51]
	v_mfma_f32_16x16x32_bf16 v[36:39], v[148:151], v[202:205], v[36:39]
	v_mfma_f32_16x16x32_bf16 v[32:35], v[156:159], v[202:205], v[32:35]
	v_mfma_f32_16x16x32_bf16 v[20:23], v[148:151], v[210:213], v[20:23]
	v_mfma_f32_16x16x32_bf16 v[16:19], v[156:159], v[210:213], v[16:19]
	v_mfma_f32_16x16x32_bf16 v[4:7], v[148:151], v[218:221], v[4:7]
	v_mfma_f32_16x16x32_bf16 v[0:3], v[156:159], v[218:221], v[0:3]
	s_barrier
	s_setprio 0
	s_add_i32 s52, 0, 0x18000
	s_add_i32 s53, 0, 0x1c000
	v_add_u32_e32 v140, s52, v188
	v_add_u32_e32 v156, s53, v188
	ds_read_b128 v[128:131], v140
	ds_read_b128 v[132:135], v140 offset:1024
	ds_read_b128 v[136:139], v140 offset:2048
	ds_read_b128 v[140:143], v140 offset:3072
	ds_read_b128 v[144:147], v156
	ds_read_b128 v[148:151], v156 offset:1024
	ds_read_b128 v[152:155], v156 offset:2048
	ds_read_b128 v[156:159], v156 offset:3072
	s_add_u32 s28, s28, 0x80000
	s_addc_u32 s29, s29, 0
	s_mov_b32 m0, s35
	v_lshl_add_u64 v[228:229], s[28:29], 0, v[162:163]
	ds_read_b128 v[180:183], v192 offset:32768
	ds_read_b128 v[194:197], v192 offset:33792
	ds_read_b128 v[198:201], v192 offset:34816
	ds_read_b128 v[202:205], v192 offset:35840
	ds_read_b128 v[206:209], v192 offset:36864
	ds_read_b128 v[210:213], v192 offset:37888
	ds_read_b128 v[214:217], v192 offset:38912
	ds_read_b128 v[218:221], v192 offset:39936
	global_load_lds_dwordx4 v[228:229], off
	v_lshl_add_u64 v[228:229], s[28:29], 0, v[166:167]
	s_mov_b32 m0, s36
	s_nop 0
	global_load_lds_dwordx4 v[228:229], off
	s_setprio 1
	s_waitcnt vmcnt(8)
	s_waitcnt lgkmcnt(0)
	s_barrier
	v_mfma_f32_16x16x32_bf16 v[124:127], v[128:131], v[180:183], v[124:127]
	v_mfma_f32_16x16x32_bf16 v[120:123], v[136:139], v[180:183], v[120:123]
	v_mfma_f32_16x16x32_bf16 v[108:111], v[128:131], v[198:201], v[108:111]
	v_mfma_f32_16x16x32_bf16 v[104:107], v[136:139], v[198:201], v[104:107]
	v_mfma_f32_16x16x32_bf16 v[92:95], v[128:131], v[206:209], v[92:95]
	v_mfma_f32_16x16x32_bf16 v[88:91], v[136:139], v[206:209], v[88:91]
	v_mfma_f32_16x16x32_bf16 v[76:79], v[128:131], v[214:217], v[76:79]
	v_mfma_f32_16x16x32_bf16 v[72:75], v[136:139], v[214:217], v[72:75]
	v_mfma_f32_16x16x32_bf16 v[124:127], v[132:135], v[194:197], v[124:127]
	v_mfma_f32_16x16x32_bf16 v[120:123], v[140:143], v[194:197], v[120:123]
	v_mfma_f32_16x16x32_bf16 v[108:111], v[132:135], v[202:205], v[108:111]
	v_mfma_f32_16x16x32_bf16 v[104:107], v[140:143], v[202:205], v[104:107]
	v_mfma_f32_16x16x32_bf16 v[92:95], v[132:135], v[210:213], v[92:95]
	v_mfma_f32_16x16x32_bf16 v[88:91], v[140:143], v[210:213], v[88:91]
	v_mfma_f32_16x16x32_bf16 v[76:79], v[132:135], v[218:221], v[76:79]
	v_mfma_f32_16x16x32_bf16 v[72:75], v[140:143], v[218:221], v[72:75]
	s_setprio 0
	s_setprio 1
	v_mfma_f32_16x16x32_bf16 v[116:119], v[144:147], v[180:183], v[116:119]
	v_mfma_f32_16x16x32_bf16 v[112:115], v[152:155], v[180:183], v[112:115]
	v_mfma_f32_16x16x32_bf16 v[100:103], v[144:147], v[198:201], v[100:103]
	v_mfma_f32_16x16x32_bf16 v[96:99], v[152:155], v[198:201], v[96:99]
	v_mfma_f32_16x16x32_bf16 v[84:87], v[144:147], v[206:209], v[84:87]
	v_mfma_f32_16x16x32_bf16 v[80:83], v[152:155], v[206:209], v[80:83]
	v_mfma_f32_16x16x32_bf16 v[68:71], v[144:147], v[214:217], v[68:71]
	v_mfma_f32_16x16x32_bf16 v[64:67], v[152:155], v[214:217], v[64:67]
	v_mfma_f32_16x16x32_bf16 v[116:119], v[148:151], v[194:197], v[116:119]
	v_mfma_f32_16x16x32_bf16 v[112:115], v[156:159], v[194:197], v[112:115]
	v_mfma_f32_16x16x32_bf16 v[100:103], v[148:151], v[202:205], v[100:103]
	v_mfma_f32_16x16x32_bf16 v[96:99], v[156:159], v[202:205], v[96:99]
	v_mfma_f32_16x16x32_bf16 v[84:87], v[148:151], v[210:213], v[84:87]
	v_mfma_f32_16x16x32_bf16 v[80:83], v[156:159], v[210:213], v[80:83]
	v_mfma_f32_16x16x32_bf16 v[68:71], v[148:151], v[218:221], v[68:71]
	v_mfma_f32_16x16x32_bf16 v[64:67], v[156:159], v[218:221], v[64:67]
	s_barrier
; #define PG8_STAGE(bufoff, gbase, voff) do { _Pragma("unroll") for (int _i = 0; _i < 2; ++_i) \
;         __builtin_amdgcn_global_load_lds((const unsigned*)((const char*)(gbase) + (voff)[_i]), (PG8_LAS unsigned*)(lds + (bufoff) + ldsw + _i * 8192), 16, 0, 0); } while (0)
;     __device__ __forceinline__ void operator()(const f32x4 (&acc)[2][2][4][2], const Unit& u, int wr, int wc, int fr, int fq) const {
;         const int pn = u.pn, row0 = u.pm * BM + wr * 64 + fr, colt = pn * BM + wc * 32 + 8 * fq;
;         if (pn >= 4 && pn < 8) {
; template <class Epi, class Sched, bool ALIGN_EPI = false, bool SP2 = false>
; __device__ __forceinline__ void gemm_phase(PG8_LAS unsigned char* lds, const Gemm g, const Sched& S, const Epi& E) {
;     ...
;             PG8_LDA(At, 1, 1); PG8_STAGE(PG8_SB(1, 0), b3, voffB); PG8_STAGE(PG8_SB(1, 1), b3 + hstep, voffB); PG8_STAGE(PG8_SA(1, 0), a3, voffA);
;             PG8_WAIT_V(8); PG8_WAIT_L(0); PG8_BAR; PG8_MMA(1, 0, At, B0); PG8_MMA(1, 1, At, B1); PG8_BAR; PG8_SCHED;
;             } else {
;             PG8_LDB(B0, 0, 0); PG8_SCHED; PG8_LDA(At, 0, 0); PG8_STAGE(PG8_SA(1, 1), a1 + hstep, voffA);
;             PG8_WAIT_L(8); PG8_BAR; PG8_WAIT_L(0); PG8_MMA(0, 0, At, B0); PG8_BAR; PG8_SCHED;
;             PG8_LDB(B1, 0, 1); PG8_STAGE(PG8_SB(0, 0), b2, voffB);
;             PG8_BAR; PG8_WAIT_L(0); PG8_MMA(0, 1, At, B1); PG8_BAR;
;             PG8_LDA(At, 0, 1); PG8_STAGE(PG8_SA(0, 0), a2, voffA);
;             PG8_BAR; PG8_WAIT_L(0); PG8_MMA(1, 0, At, B0); PG8_BAR; PG8_SCHED;
;             PG8_STAGE(PG8_SB(0, 1), b2 + hstep, voffB);
;             PG8_WAIT_V(6); PG8_BAR; PG8_MMA(1, 1, At, B1); PG8_BAR;
;             PG8_LDB(B0, 1, 0); PG8_SCHED; PG8_LDA(At, 1, 0); PG8_STAGE(PG8_SA(0, 1), a2 + hstep, voffA);
;             PG8_WAIT_L(8); PG8_BAR; PG8_WAIT_L(0); PG8_MMA(0, 0, At, B0); PG8_BAR; PG8_SCHED;
;             PG8_LDB(B1, 1, 1); PG8_STAGE(PG8_SB(1, 0), b3, voffB);
;             PG8_BAR; PG8_WAIT_L(0); PG8_MMA(0, 1, At, B1); PG8_BAR;
;             PG8_LDA(At, 1, 1); PG8_STAGE(PG8_SA(1, 0), a3, voffA);
;             PG8_BAR; PG8_WAIT_L(0); PG8_MMA(1, 0, At, B0); PG8_BAR; PG8_SCHED;
;             PG8_STAGE(PG8_SB(1, 1), b3 + hstep, voffB);
;             PG8_WAIT_V(6); PG8_BAR; PG8_MMA(1, 1, At, B1); PG8_BAR;
;             }
;         }
;         if constexpr (ALIGN_EPI) { if (wr == 0) PG8_BAR; }
	s_setprio 0
	s_add_i32 s28, s52, s30
	v_lshl_add_u64 v[184:185], v[184:185], 0, s[16:17]
	s_mov_b32 m0, s28
	ds_read_b128 v[180:183], v192 offset:49152
	ds_read_b128 v[194:197], v192 offset:50176
	ds_read_b128 v[198:201], v192 offset:51200
	ds_read_b128 v[202:205], v192 offset:52224
	ds_read_b128 v[206:209], v192 offset:53248
	ds_read_b128 v[210:213], v192 offset:54272
	ds_read_b128 v[214:217], v192 offset:55296
	ds_read_b128 v[218:221], v192 offset:56320
	global_load_lds_dwordx4 v[184:185], off
	s_add_i32 m0, s28, 0x2000
	s_add_u32 s6, s6, 0x80080
	v_lshl_add_u64 v[184:185], v[222:223], 0, s[16:17]
	s_addc_u32 s7, s7, 0
	s_add_i32 s28, s53, s30
	global_load_lds_dwordx4 v[184:185], off
	v_lshl_add_u64 v[184:185], s[6:7], 0, v[164:165]
	s_mov_b32 m0, s28
	s_nop 0
	global_load_lds_dwordx4 v[184:185], off
	v_lshl_add_u64 v[184:185], s[6:7], 0, v[168:169]
	s_add_i32 m0, s28, 0x2000
	s_nop 0
	global_load_lds_dwordx4 v[184:185], off
	v_lshl_add_u64 v[184:185], v[224:225], 0, s[16:17]
	s_mov_b32 m0, s38
	s_nop 0
	global_load_lds_dwordx4 v[184:185], off
	v_lshl_add_u64 v[184:185], v[226:227], 0, s[16:17]
	s_mov_b32 m0, s39
	s_nop 0
	global_load_lds_dwordx4 v[184:185], off
	s_setprio 1
	s_waitcnt vmcnt(8)
	s_waitcnt lgkmcnt(0)
	s_barrier
	v_mfma_f32_16x16x32_bf16 v[60:63], v[128:131], v[180:183], v[60:63]
	v_mfma_f32_16x16x32_bf16 v[56:59], v[136:139], v[180:183], v[56:59]
	v_mfma_f32_16x16x32_bf16 v[44:47], v[128:131], v[198:201], v[44:47]
	v_mfma_f32_16x16x32_bf16 v[40:43], v[136:139], v[198:201], v[40:43]
	v_mfma_f32_16x16x32_bf16 v[28:31], v[128:131], v[206:209], v[28:31]
	v_mfma_f32_16x16x32_bf16 v[24:27], v[136:139], v[206:209], v[24:27]
	v_mfma_f32_16x16x32_bf16 v[12:15], v[128:131], v[214:217], v[12:15]
	v_mfma_f32_16x16x32_bf16 v[8:11], v[136:139], v[214:217], v[8:11]
	v_mfma_f32_16x16x32_bf16 v[60:63], v[132:135], v[194:197], v[60:63]
	v_mfma_f32_16x16x32_bf16 v[56:59], v[140:143], v[194:197], v[56:59]
	v_mfma_f32_16x16x32_bf16 v[44:47], v[132:135], v[202:205], v[44:47]
	v_mfma_f32_16x16x32_bf16 v[40:43], v[140:143], v[202:205], v[40:43]
	v_mfma_f32_16x16x32_bf16 v[28:31], v[132:135], v[210:213], v[28:31]
	v_mfma_f32_16x16x32_bf16 v[24:27], v[140:143], v[210:213], v[24:27]
	v_mfma_f32_16x16x32_bf16 v[12:15], v[132:135], v[218:221], v[12:15]
	v_mfma_f32_16x16x32_bf16 v[8:11], v[140:143], v[218:221], v[8:11]
	s_setprio 0
	s_setprio 1
	v_mfma_f32_16x16x32_bf16 v[52:55], v[144:147], v[180:183], v[52:55]
	v_mfma_f32_16x16x32_bf16 v[48:51], v[152:155], v[180:183], v[48:51]
	v_mfma_f32_16x16x32_bf16 v[36:39], v[144:147], v[198:201], v[36:39]
	v_mfma_f32_16x16x32_bf16 v[32:35], v[152:155], v[198:201], v[32:35]
	v_mfma_f32_16x16x32_bf16 v[20:23], v[144:147], v[206:209], v[20:23]
	v_mfma_f32_16x16x32_bf16 v[16:19], v[152:155], v[206:209], v[16:19]
	v_mfma_f32_16x16x32_bf16 v[4:7], v[144:147], v[214:217], v[4:7]
	v_mfma_f32_16x16x32_bf16 v[0:3], v[152:155], v[214:217], v[0:3]
	v_mfma_f32_16x16x32_bf16 v[52:55], v[148:151], v[194:197], v[52:55]
	v_mfma_f32_16x16x32_bf16 v[48:51], v[156:159], v[194:197], v[48:51]
	v_mfma_f32_16x16x32_bf16 v[36:39], v[148:151], v[202:205], v[36:39]
	v_mfma_f32_16x16x32_bf16 v[32:35], v[156:159], v[202:205], v[32:35]
	v_mfma_f32_16x16x32_bf16 v[20:23], v[148:151], v[210:213], v[20:23]
	v_mfma_f32_16x16x32_bf16 v[16:19], v[156:159], v[210:213], v[16:19]
	v_mfma_f32_16x16x32_bf16 v[4:7], v[148:151], v[218:221], v[4:7]
	v_mfma_f32_16x16x32_bf16 v[0:3], v[156:159], v[218:221], v[0:3]
	s_barrier
	s_setprio 0
	s_add_i32 s51, s51, 2
	s_add_u32 s4, s4, 0x100
	s_addc_u32 s5, s5, 0
	s_add_u32 s33, s33, 0x100
	s_addc_u32 s50, s50, 0
	s_cmp_gt_u32 s51, 29
	s_cbranch_scc0 .LBB0_205
	s_and_b64 vcc, exec, s[18:19]
	s_cbranch_vccz .LBB0_208
.LBB0_208:
	s_and_b32 s1, s0, -4
	v_lshl_add_u32 v182, s2, 8, v161
	v_lshl_or_b32 v170, s0, 8, v189
	s_cmp_lg_u32 s1, 4
	s_mov_b64 s[2:3], -1
	s_cbranch_scc1 .LBB0_211
	s_and_b64 vcc, exec, s[2:3]
	s_cbranch_vccnz .LBB0_260
